# SwiGLU epilogue math: h = (g*u)*rcp((1+2^(c*g))*v) with c=-log2e*rsqrt(v), 6 f32 VALU ops per element instead of 8 (no packed ops)
# speedup vs baseline: 1.0678x; 1.0036x over previous
.LBB0_547:
	v_lshl_add_u32 v144, s36, 8, v152
	v_ashrrev_i32_e32 v145, 31, v144
	v_lshl_add_u64 v[150:151], v[144:145], 2, s[10:11]
	global_load_dword v244, v[150:151], off
	global_load_dword v245, v[150:151], off offset:64
	global_load_dword v246, v[150:151], off offset:128
	global_load_dword v247, v[150:151], off offset:192
	global_load_dword v248, v[150:151], off offset:512
	global_load_dword v249, v[150:151], off offset:576
	global_load_dword v250, v[150:151], off offset:640
	global_load_dword v251, v[150:151], off offset:704
	v_or_b32_e32 v162, 16, v144
	v_ashrrev_i32_e32 v163, 31, v162
	v_lshl_add_u64 v[166:167], v[162:163], 2, s[10:11]
	v_lshl_or_b32 v148, s33, 7, v154
	v_mov_b64_e32 v[146:147], s[12:13]
	v_ashrrev_i32_e32 v149, 31, v148
	v_mad_i64_i32 v[160:161], s[38:39], v144, s58, v[146:147]
	v_lshlrev_b64 v[148:149], 1, v[148:149]
	v_lshl_add_u64 v[160:161], v[160:161], 0, v[148:149]
	s_andn2_b64 vcc, exec, s[4:5]
	s_mov_b64 s[4:5], -1
	s_waitcnt vmcnt(0)
	v_fmamk_f32 v243, v244, 0x3a800000, v158
	v_rsq_f32_e32 v252, v243
	s_nop 0
	v_mul_f32_e32 v252, 0xbfb8aa3b, v252
	v_mul_f32_e32 v116, v124, v116
	v_mul_f32_e32 v117, v125, v117
	v_mul_f32_e32 v118, v126, v118
	v_mul_f32_e32 v119, v127, v119
	v_mul_f32_e32 v112, v120, v112
	v_mul_f32_e32 v113, v121, v113
	v_mul_f32_e32 v114, v122, v114
	v_mul_f32_e32 v115, v123, v115
	v_mul_f32_e32 v124, v252, v124
	v_mul_f32_e32 v125, v252, v125
	v_mul_f32_e32 v126, v252, v126
	v_mul_f32_e32 v127, v252, v127
	v_mul_f32_e32 v120, v252, v120
	v_mul_f32_e32 v121, v252, v121
	v_mul_f32_e32 v122, v252, v122
	v_mul_f32_e32 v123, v252, v123
	v_exp_f32_e32 v124, v124
	v_exp_f32_e32 v125, v125
	v_exp_f32_e32 v126, v126
	v_exp_f32_e32 v127, v127
	v_exp_f32_e32 v120, v120
	v_exp_f32_e32 v121, v121
	v_exp_f32_e32 v122, v122
	v_exp_f32_e32 v123, v123
	v_fma_f32 v124, v124, v243, v243
	v_fma_f32 v125, v125, v243, v243
	v_fma_f32 v126, v126, v243, v243
	v_fma_f32 v127, v127, v243, v243
	v_fma_f32 v120, v120, v243, v243
	v_fma_f32 v121, v121, v243, v243
	v_fma_f32 v122, v122, v243, v243
	v_fma_f32 v123, v123, v243, v243
	v_rcp_f32_e32 v124, v124
	v_rcp_f32_e32 v125, v125
	v_rcp_f32_e32 v126, v126
	v_rcp_f32_e32 v127, v127
	v_rcp_f32_e32 v120, v120
	v_rcp_f32_e32 v121, v121
	v_rcp_f32_e32 v122, v122
	v_rcp_f32_e32 v123, v123
	v_mul_f32_e32 v116, v116, v124
	v_mul_f32_e32 v117, v117, v125
	v_mul_f32_e32 v118, v118, v126
	v_mul_f32_e32 v119, v119, v127
	v_mul_f32_e32 v120, v112, v120
	v_mul_f32_e32 v121, v113, v121
	v_mul_f32_e32 v122, v114, v122
	v_mul_f32_e32 v123, v115, v123
	v_cvt_pk_bf16_f32 v112, v116, v117
	v_cvt_pk_bf16_f32 v113, v118, v119
	v_cvt_pk_bf16_f32 v114, v120, v121
	v_cvt_pk_bf16_f32 v115, v122, v123
	global_store_dwordx4 v[160:161], v[112:115], off
	s_nop 0
	s_nop 0
	v_or_b32_e32 v112, 32, v144
	v_mad_i64_i32 v[114:115], s[38:39], v162, s58, v[146:147]
	v_lshl_add_u64 v[114:115], v[114:115], 0, v[148:149]
	v_fmamk_f32 v243, v245, 0x3a800000, v158
	v_rsq_f32_e32 v252, v243
	v_ashrrev_i32_e32 v113, 31, v112
	v_lshl_add_u64 v[118:119], v[112:113], 2, s[10:11]
	s_nop 0
	v_mul_f32_e32 v252, 0xbfb8aa3b, v252
	v_mul_f32_e32 v100, v108, v100
	v_mul_f32_e32 v101, v109, v101
	v_mul_f32_e32 v102, v110, v102
	v_mul_f32_e32 v103, v111, v103
	v_mul_f32_e32 v96, v104, v96
	v_mul_f32_e32 v97, v105, v97
	v_mul_f32_e32 v98, v106, v98
	v_mul_f32_e32 v99, v107, v99
	v_mul_f32_e32 v108, v252, v108
	v_mul_f32_e32 v109, v252, v109
	v_mul_f32_e32 v110, v252, v110
	v_mul_f32_e32 v111, v252, v111
	v_mul_f32_e32 v104, v252, v104
	v_mul_f32_e32 v105, v252, v105
	v_mul_f32_e32 v106, v252, v106
	v_mul_f32_e32 v107, v252, v107
	v_exp_f32_e32 v108, v108
	v_exp_f32_e32 v109, v109
	v_exp_f32_e32 v110, v110
	v_exp_f32_e32 v111, v111
	v_exp_f32_e32 v104, v104
	v_exp_f32_e32 v105, v105
	v_exp_f32_e32 v106, v106
	v_exp_f32_e32 v107, v107
	v_fma_f32 v108, v108, v243, v243
	v_fma_f32 v109, v109, v243, v243
	v_fma_f32 v110, v110, v243, v243
	v_fma_f32 v111, v111, v243, v243
	v_fma_f32 v104, v104, v243, v243
	v_fma_f32 v105, v105, v243, v243
	v_fma_f32 v106, v106, v243, v243
	v_fma_f32 v107, v107, v243, v243
	v_rcp_f32_e32 v108, v108
	v_rcp_f32_e32 v109, v109
	v_rcp_f32_e32 v110, v110
	v_rcp_f32_e32 v111, v111
	v_rcp_f32_e32 v104, v104
	v_rcp_f32_e32 v105, v105
	v_rcp_f32_e32 v106, v106
	v_rcp_f32_e32 v107, v107
	v_mul_f32_e32 v100, v100, v108
	v_mul_f32_e32 v101, v101, v109
	v_mul_f32_e32 v102, v102, v110
	v_mul_f32_e32 v103, v103, v111
	v_mul_f32_e32 v104, v96, v104
	v_mul_f32_e32 v105, v97, v105
	v_mul_f32_e32 v106, v98, v106
	v_mul_f32_e32 v107, v99, v107
	v_cvt_pk_bf16_f32 v96, v100, v101
	v_cvt_pk_bf16_f32 v97, v102, v103
	v_cvt_pk_bf16_f32 v98, v104, v105
	v_cvt_pk_bf16_f32 v99, v106, v107
	global_store_dwordx4 v[114:115], v[96:99], off
	s_nop 0
	s_nop 0
	v_or_b32_e32 v96, 48, v144
	v_mad_i64_i32 v[98:99], s[38:39], v112, s58, v[146:147]
	v_lshl_add_u64 v[98:99], v[98:99], 0, v[148:149]
	v_fmamk_f32 v243, v246, 0x3a800000, v158
	v_rsq_f32_e32 v252, v243
	v_ashrrev_i32_e32 v97, 31, v96
	v_lshl_add_u64 v[102:103], v[96:97], 2, s[10:11]
	s_nop 0
	v_mul_f32_e32 v252, 0xbfb8aa3b, v252
	v_mul_f32_e32 v84, v92, v84
	v_mul_f32_e32 v85, v93, v85
	v_mul_f32_e32 v86, v94, v86
	v_mul_f32_e32 v87, v95, v87
	v_mul_f32_e32 v80, v88, v80
	v_mul_f32_e32 v81, v89, v81
	v_mul_f32_e32 v82, v90, v82
	v_mul_f32_e32 v83, v91, v83
	v_mul_f32_e32 v92, v252, v92
	v_mul_f32_e32 v93, v252, v93
	v_mul_f32_e32 v94, v252, v94
	v_mul_f32_e32 v95, v252, v95
	v_mul_f32_e32 v88, v252, v88
	v_mul_f32_e32 v89, v252, v89
	v_mul_f32_e32 v90, v252, v90
	v_mul_f32_e32 v91, v252, v91
	v_exp_f32_e32 v92, v92
	v_exp_f32_e32 v93, v93
	v_exp_f32_e32 v94, v94
	v_exp_f32_e32 v95, v95
	v_exp_f32_e32 v88, v88
	v_exp_f32_e32 v89, v89
	v_exp_f32_e32 v90, v90
	v_exp_f32_e32 v91, v91
	v_fma_f32 v92, v92, v243, v243
	v_fma_f32 v93, v93, v243, v243
	v_fma_f32 v94, v94, v243, v243
	v_fma_f32 v95, v95, v243, v243
	v_fma_f32 v88, v88, v243, v243
	v_fma_f32 v89, v89, v243, v243
	v_fma_f32 v90, v90, v243, v243
	v_fma_f32 v91, v91, v243, v243
	v_rcp_f32_e32 v92, v92
	v_rcp_f32_e32 v93, v93
	v_rcp_f32_e32 v94, v94
	v_rcp_f32_e32 v95, v95
	v_rcp_f32_e32 v88, v88
	v_rcp_f32_e32 v89, v89
	v_rcp_f32_e32 v90, v90
	v_rcp_f32_e32 v91, v91
	v_mul_f32_e32 v84, v84, v92
	v_mul_f32_e32 v85, v85, v93
	v_mul_f32_e32 v86, v86, v94
	v_mul_f32_e32 v87, v87, v95
	v_mul_f32_e32 v88, v80, v88
	v_mul_f32_e32 v89, v81, v89
	v_mul_f32_e32 v90, v82, v90
	v_mul_f32_e32 v91, v83, v91
	v_cvt_pk_bf16_f32 v80, v84, v85
	v_cvt_pk_bf16_f32 v81, v86, v87
	v_cvt_pk_bf16_f32 v82, v88, v89
	v_cvt_pk_bf16_f32 v83, v90, v91
	global_store_dwordx4 v[98:99], v[80:83], off
	s_nop 0
	s_nop 0
	v_mad_i64_i32 v[82:83], s[38:39], v96, s58, v[146:147]
	v_lshl_add_u64 v[82:83], v[82:83], 0, v[148:149]
	v_fmamk_f32 v243, v247, 0x3a800000, v158
	v_rsq_f32_e32 v252, v243
	s_nop 0
	v_mul_f32_e32 v252, 0xbfb8aa3b, v252
	v_mul_f32_e32 v68, v76, v68
	v_mul_f32_e32 v69, v77, v69
	v_mul_f32_e32 v70, v78, v70
	v_mul_f32_e32 v71, v79, v71
	v_mul_f32_e32 v64, v72, v64
	v_mul_f32_e32 v65, v73, v65
	v_mul_f32_e32 v66, v74, v66
	v_mul_f32_e32 v67, v75, v67
	v_mul_f32_e32 v76, v252, v76
	v_mul_f32_e32 v77, v252, v77
	v_mul_f32_e32 v78, v252, v78
	v_mul_f32_e32 v79, v252, v79
	v_mul_f32_e32 v72, v252, v72
	v_mul_f32_e32 v73, v252, v73
	v_mul_f32_e32 v74, v252, v74
	v_mul_f32_e32 v75, v252, v75
	v_exp_f32_e32 v76, v76
	v_exp_f32_e32 v77, v77
	v_exp_f32_e32 v78, v78
	v_exp_f32_e32 v79, v79
	v_exp_f32_e32 v72, v72
	v_exp_f32_e32 v73, v73
	v_exp_f32_e32 v74, v74
	v_exp_f32_e32 v75, v75
	v_fma_f32 v76, v76, v243, v243
	v_fma_f32 v77, v77, v243, v243
	v_fma_f32 v78, v78, v243, v243
	v_fma_f32 v79, v79, v243, v243
	v_fma_f32 v72, v72, v243, v243
	v_fma_f32 v73, v73, v243, v243
	v_fma_f32 v74, v74, v243, v243
	v_fma_f32 v75, v75, v243, v243
	v_rcp_f32_e32 v76, v76
	v_rcp_f32_e32 v77, v77
	v_rcp_f32_e32 v78, v78
	v_rcp_f32_e32 v79, v79
	v_rcp_f32_e32 v72, v72
	v_rcp_f32_e32 v73, v73
	v_rcp_f32_e32 v74, v74
	v_rcp_f32_e32 v75, v75
	v_mul_f32_e32 v68, v68, v76
	v_mul_f32_e32 v69, v69, v77
	v_mul_f32_e32 v70, v70, v78
	v_mul_f32_e32 v71, v71, v79
	v_mul_f32_e32 v72, v64, v72
	v_mul_f32_e32 v73, v65, v73
	v_mul_f32_e32 v74, v66, v74
	v_mul_f32_e32 v75, v67, v75
	v_cvt_pk_bf16_f32 v64, v68, v69
	v_cvt_pk_bf16_f32 v65, v70, v71
	v_cvt_pk_bf16_f32 v66, v72, v73
	v_cvt_pk_bf16_f32 v67, v74, v75
	global_store_dwordx4 v[82:83], v[64:67], off
	s_nop 0
	s_nop 0
	v_add_u32_e32 v65, 0x80, v144
	v_mad_i64_i32 v[66:67], s[38:39], v65, s58, v[146:147]
	v_lshl_add_u64 v[66:67], v[66:67], 0, v[148:149]
	v_fmamk_f32 v243, v248, 0x3a800000, v158
	v_rsq_f32_e32 v252, v243
	s_nop 0
	v_mul_f32_e32 v252, 0xbfb8aa3b, v252
	v_mul_f32_e32 v52, v60, v52
	v_mul_f32_e32 v53, v61, v53
	v_mul_f32_e32 v54, v62, v54
	v_mul_f32_e32 v55, v63, v55
	v_mul_f32_e32 v48, v56, v48
	v_mul_f32_e32 v49, v57, v49
	v_mul_f32_e32 v50, v58, v50
	v_mul_f32_e32 v51, v59, v51
	v_mul_f32_e32 v60, v252, v60
	v_mul_f32_e32 v61, v252, v61
	v_mul_f32_e32 v62, v252, v62
	v_mul_f32_e32 v63, v252, v63
	v_mul_f32_e32 v56, v252, v56
	v_mul_f32_e32 v57, v252, v57
	v_mul_f32_e32 v58, v252, v58
	v_mul_f32_e32 v59, v252, v59
	v_exp_f32_e32 v60, v60
	v_exp_f32_e32 v61, v61
	v_exp_f32_e32 v62, v62
	v_exp_f32_e32 v63, v63
	v_exp_f32_e32 v56, v56
	v_exp_f32_e32 v57, v57
	v_exp_f32_e32 v58, v58
	v_exp_f32_e32 v59, v59
	v_fma_f32 v60, v60, v243, v243
	v_fma_f32 v61, v61, v243, v243
	v_fma_f32 v62, v62, v243, v243
	v_fma_f32 v63, v63, v243, v243
	v_fma_f32 v56, v56, v243, v243
	v_fma_f32 v57, v57, v243, v243
	v_fma_f32 v58, v58, v243, v243
	v_fma_f32 v59, v59, v243, v243
	v_rcp_f32_e32 v60, v60
	v_rcp_f32_e32 v61, v61
	v_rcp_f32_e32 v62, v62
	v_rcp_f32_e32 v63, v63
	v_rcp_f32_e32 v56, v56
	v_rcp_f32_e32 v57, v57
	v_rcp_f32_e32 v58, v58
	v_rcp_f32_e32 v59, v59
	v_mul_f32_e32 v52, v52, v60
	v_mul_f32_e32 v53, v53, v61
	v_mul_f32_e32 v54, v54, v62
	v_mul_f32_e32 v55, v55, v63
	v_mul_f32_e32 v56, v48, v56
	v_mul_f32_e32 v57, v49, v57
	v_mul_f32_e32 v58, v50, v58
	v_mul_f32_e32 v59, v51, v59
	v_cvt_pk_bf16_f32 v48, v52, v53
	v_cvt_pk_bf16_f32 v49, v54, v55
	v_cvt_pk_bf16_f32 v50, v56, v57
	v_cvt_pk_bf16_f32 v51, v58, v59
	global_store_dwordx4 v[66:67], v[48:51], off
	s_nop 0
	s_nop 0
	v_add_u32_e32 v49, 0x90, v144
	v_mad_i64_i32 v[50:51], s[38:39], v49, s58, v[146:147]
	v_lshl_add_u64 v[50:51], v[50:51], 0, v[148:149]
	v_fmamk_f32 v243, v249, 0x3a800000, v158
	v_rsq_f32_e32 v252, v243
	s_nop 0
	v_mul_f32_e32 v252, 0xbfb8aa3b, v252
	v_mul_f32_e32 v36, v44, v36
	v_mul_f32_e32 v37, v45, v37
	v_mul_f32_e32 v38, v46, v38
	v_mul_f32_e32 v39, v47, v39
	v_mul_f32_e32 v32, v40, v32
	v_mul_f32_e32 v33, v41, v33
	v_mul_f32_e32 v34, v42, v34
	v_mul_f32_e32 v35, v43, v35
	v_mul_f32_e32 v44, v252, v44
	v_mul_f32_e32 v45, v252, v45
	v_mul_f32_e32 v46, v252, v46
	v_mul_f32_e32 v47, v252, v47
	v_mul_f32_e32 v40, v252, v40
	v_mul_f32_e32 v41, v252, v41
	v_mul_f32_e32 v42, v252, v42
	v_mul_f32_e32 v43, v252, v43
	v_exp_f32_e32 v44, v44
	v_exp_f32_e32 v45, v45
	v_exp_f32_e32 v46, v46
	v_exp_f32_e32 v47, v47
	v_exp_f32_e32 v40, v40
	v_exp_f32_e32 v41, v41
	v_exp_f32_e32 v42, v42
	v_exp_f32_e32 v43, v43
	v_fma_f32 v44, v44, v243, v243
	v_fma_f32 v45, v45, v243, v243
	v_fma_f32 v46, v46, v243, v243
	v_fma_f32 v47, v47, v243, v243
	v_fma_f32 v40, v40, v243, v243
	v_fma_f32 v41, v41, v243, v243
	v_fma_f32 v42, v42, v243, v243
	v_fma_f32 v43, v43, v243, v243
	v_rcp_f32_e32 v44, v44
	v_rcp_f32_e32 v45, v45
	v_rcp_f32_e32 v46, v46
	v_rcp_f32_e32 v47, v47
	v_rcp_f32_e32 v40, v40
	v_rcp_f32_e32 v41, v41
	v_rcp_f32_e32 v42, v42
	v_rcp_f32_e32 v43, v43
	v_mul_f32_e32 v36, v36, v44
	v_mul_f32_e32 v37, v37, v45
	v_mul_f32_e32 v38, v38, v46
	v_mul_f32_e32 v39, v39, v47
	v_mul_f32_e32 v40, v32, v40
	v_mul_f32_e32 v41, v33, v41
	v_mul_f32_e32 v42, v34, v42
	v_mul_f32_e32 v43, v35, v43
	v_cvt_pk_bf16_f32 v32, v36, v37
	v_cvt_pk_bf16_f32 v33, v38, v39
	v_cvt_pk_bf16_f32 v34, v40, v41
	v_cvt_pk_bf16_f32 v35, v42, v43
	global_store_dwordx4 v[50:51], v[32:35], off
	s_nop 0
	s_nop 0
	v_add_u32_e32 v33, 0xa0, v144
	v_mad_i64_i32 v[34:35], s[38:39], v33, s58, v[146:147]
	v_lshl_add_u64 v[34:35], v[34:35], 0, v[148:149]
	v_fmamk_f32 v243, v250, 0x3a800000, v158
	v_rsq_f32_e32 v252, v243
	s_nop 0
	v_mul_f32_e32 v252, 0xbfb8aa3b, v252
	v_mul_f32_e32 v20, v28, v20
	v_mul_f32_e32 v21, v29, v21
	v_mul_f32_e32 v22, v30, v22
	v_mul_f32_e32 v23, v31, v23
	v_mul_f32_e32 v16, v24, v16
	v_mul_f32_e32 v17, v25, v17
	v_mul_f32_e32 v18, v26, v18
	v_mul_f32_e32 v19, v27, v19
	v_mul_f32_e32 v28, v252, v28
	v_mul_f32_e32 v29, v252, v29
	v_mul_f32_e32 v30, v252, v30
	v_mul_f32_e32 v31, v252, v31
	v_mul_f32_e32 v24, v252, v24
	v_mul_f32_e32 v25, v252, v25
	v_mul_f32_e32 v26, v252, v26
	v_mul_f32_e32 v27, v252, v27
	v_exp_f32_e32 v28, v28
	v_exp_f32_e32 v29, v29
	v_exp_f32_e32 v30, v30
	v_exp_f32_e32 v31, v31
	v_exp_f32_e32 v24, v24
	v_exp_f32_e32 v25, v25
	v_exp_f32_e32 v26, v26
	v_exp_f32_e32 v27, v27
	v_fma_f32 v28, v28, v243, v243
	v_fma_f32 v29, v29, v243, v243
	v_fma_f32 v30, v30, v243, v243
	v_fma_f32 v31, v31, v243, v243
	v_fma_f32 v24, v24, v243, v243
	v_fma_f32 v25, v25, v243, v243
	v_fma_f32 v26, v26, v243, v243
	v_fma_f32 v27, v27, v243, v243
	v_rcp_f32_e32 v28, v28
	v_rcp_f32_e32 v29, v29
	v_rcp_f32_e32 v30, v30
	v_rcp_f32_e32 v31, v31
	v_rcp_f32_e32 v24, v24
	v_rcp_f32_e32 v25, v25
	v_rcp_f32_e32 v26, v26
	v_rcp_f32_e32 v27, v27
	v_mul_f32_e32 v20, v20, v28
	v_mul_f32_e32 v21, v21, v29
	v_mul_f32_e32 v22, v22, v30
	v_mul_f32_e32 v23, v23, v31
	v_mul_f32_e32 v24, v16, v24
	v_mul_f32_e32 v25, v17, v25
	v_mul_f32_e32 v26, v18, v26
	v_mul_f32_e32 v27, v19, v27
	v_cvt_pk_bf16_f32 v16, v20, v21
	v_cvt_pk_bf16_f32 v17, v22, v23
	v_cvt_pk_bf16_f32 v18, v24, v25
	v_cvt_pk_bf16_f32 v19, v26, v27
	global_store_dwordx4 v[34:35], v[16:19], off
	s_nop 0
	s_nop 0
	v_add_u32_e32 v17, 0xb0, v144
	v_mad_i64_i32 v[18:19], s[38:39], v17, s58, v[146:147]
	v_lshl_add_u64 v[18:19], v[18:19], 0, v[148:149]
	v_fmamk_f32 v243, v251, 0x3a800000, v158
	v_rsq_f32_e32 v252, v243
	s_nop 0
	v_mul_f32_e32 v252, 0xbfb8aa3b, v252
	v_mul_f32_e32 v4, v12, v4
	v_mul_f32_e32 v5, v13, v5
	v_mul_f32_e32 v6, v14, v6
	v_mul_f32_e32 v7, v15, v7
	v_mul_f32_e32 v0, v8, v0
	v_mul_f32_e32 v1, v9, v1
	v_mul_f32_e32 v2, v10, v2
	v_mul_f32_e32 v3, v11, v3
	v_mul_f32_e32 v12, v252, v12
	v_mul_f32_e32 v13, v252, v13
	v_mul_f32_e32 v14, v252, v14
	v_mul_f32_e32 v15, v252, v15
	v_mul_f32_e32 v8, v252, v8
	v_mul_f32_e32 v9, v252, v9
	v_mul_f32_e32 v10, v252, v10
	v_mul_f32_e32 v11, v252, v11
	v_exp_f32_e32 v12, v12
	v_exp_f32_e32 v13, v13
	v_exp_f32_e32 v14, v14
	v_exp_f32_e32 v15, v15
	v_exp_f32_e32 v8, v8
	v_exp_f32_e32 v9, v9
	v_exp_f32_e32 v10, v10
	v_exp_f32_e32 v11, v11
	v_fma_f32 v12, v12, v243, v243
	v_fma_f32 v13, v13, v243, v243
	v_fma_f32 v14, v14, v243, v243
	v_fma_f32 v15, v15, v243, v243
	v_fma_f32 v8, v8, v243, v243
	v_fma_f32 v9, v9, v243, v243
	v_fma_f32 v10, v10, v243, v243
	v_fma_f32 v11, v11, v243, v243
	v_rcp_f32_e32 v12, v12
	v_rcp_f32_e32 v13, v13
	v_rcp_f32_e32 v14, v14
	v_rcp_f32_e32 v15, v15
	v_rcp_f32_e32 v8, v8
	v_rcp_f32_e32 v9, v9
	v_rcp_f32_e32 v10, v10
	v_rcp_f32_e32 v11, v11
	v_mul_f32_e32 v4, v4, v12
	v_mul_f32_e32 v5, v5, v13
	v_mul_f32_e32 v6, v6, v14
	v_mul_f32_e32 v7, v7, v15
	v_mul_f32_e32 v8, v0, v8
	v_mul_f32_e32 v9, v1, v9
	v_mul_f32_e32 v10, v2, v10
	v_mul_f32_e32 v11, v3, v11
	v_cvt_pk_bf16_f32 v0, v4, v5
	v_cvt_pk_bf16_f32 v1, v6, v7
	v_cvt_pk_bf16_f32 v2, v8, v9
	v_cvt_pk_bf16_f32 v3, v10, v11
	global_store_dwordx4 v[18:19], v[0:3], off
	s_cbranch_vccnz .LBB0_540
	s_andn2_b64 vcc, exec, s[8:9]
	s_cbranch_vccnz .LBB0_539
	s_barrier
	s_branch .LBB0_539

	.amdhsa_kernel _Z10fwd_kernel4Args
		.amdhsa_group_segment_fixed_size 0
		.amdhsa_private_segment_fixed_size 0
		.amdhsa_kernarg_size 424
		.amdhsa_user_sgpr_count 2
		.amdhsa_user_sgpr_dispatch_ptr 0
		.amdhsa_user_sgpr_queue_ptr 0
		.amdhsa_user_sgpr_kernarg_segment_ptr 1
		.amdhsa_user_sgpr_dispatch_id 0
		.amdhsa_user_sgpr_kernarg_preload_length 0
		.amdhsa_user_sgpr_kernarg_preload_offset 0
		.amdhsa_user_sgpr_private_segment_size 0
		.amdhsa_uses_dynamic_stack 0
		.amdhsa_enable_private_segment 0
		.amdhsa_system_sgpr_workgroup_id_x 1
		.amdhsa_system_sgpr_workgroup_id_y 0
		.amdhsa_system_sgpr_workgroup_id_z 0
		.amdhsa_system_sgpr_workgroup_info 0
		.amdhsa_system_vgpr_workitem_id 2
		.amdhsa_next_free_vgpr 253
		.amdhsa_next_free_sgpr 101
		.amdhsa_accum_offset 256
		.amdhsa_reserve_vcc 1
		.amdhsa_float_round_mode_32 0
		.amdhsa_float_round_mode_16_64 0
		.amdhsa_float_denorm_mode_32 3
		.amdhsa_float_denorm_mode_16_64 3
		.amdhsa_dx10_clamp 1
		.amdhsa_ieee_mode 1
		.amdhsa_fp16_overflow 0
		.amdhsa_tg_split 0
		.amdhsa_exception_fp_ieee_invalid_op 0
		.amdhsa_exception_fp_denorm_src 0
		.amdhsa_exception_fp_ieee_div_zero 0
		.amdhsa_exception_fp_ieee_overflow 0
		.amdhsa_exception_fp_ieee_underflow 0
		.amdhsa_exception_fp_ieee_inexact 0
		.amdhsa_exception_int_div_zero 0
	.end_amdhsa_kernel

amdhsa.kernels:
  - .agpr_count:     0
    .args:
      - .offset:         0
        .size:           168
        .value_kind:     by_value
      - .offset:         168
        .size:           4
        .value_kind:     hidden_block_count_x
      - .offset:         172
        .size:           4
        .value_kind:     hidden_block_count_y
      - .offset:         176
        .size:           4
        .value_kind:     hidden_block_count_z
      - .offset:         180
        .size:           2
        .value_kind:     hidden_group_size_x
      - .offset:         182
        .size:           2
        .value_kind:     hidden_group_size_y
      - .offset:         184
        .size:           2
        .value_kind:     hidden_group_size_z
      - .offset:         186
        .size:           2
        .value_kind:     hidden_remainder_x
      - .offset:         188
        .size:           2
        .value_kind:     hidden_remainder_y
      - .offset:         190
        .size:           2
        .value_kind:     hidden_remainder_z
      - .offset:         208
        .size:           8
        .value_kind:     hidden_global_offset_x
      - .offset:         216
        .size:           8
        .value_kind:     hidden_global_offset_y
      - .offset:         224
        .size:           8
        .value_kind:     hidden_global_offset_z
      - .offset:         232
        .size:           2
        .value_kind:     hidden_grid_dims
      - .offset:         256
        .size:           8
        .value_kind:     hidden_multigrid_sync_arg
      - .offset:         288
        .size:           4
        .value_kind:     hidden_dynamic_lds_size
    .group_segment_fixed_size: 0
    .kernarg_segment_align: 8
    .kernarg_segment_size: 424
    .language:       OpenCL C
    .language_version:
      - 2
      - 0
    .max_flat_workgroup_size: 512
    .name:           _Z10fwd_kernel4Args
    .private_segment_fixed_size: 0
    .sgpr_count:     107
    .sgpr_spill_count: 52
    .symbol:         _Z10fwd_kernel4Args.kd
    .uniform_work_group_size: 1
    .uses_dynamic_stack: false
    .vgpr_count:     253
    .vgpr_spill_count: 0
    .wavefront_size: 64
